# P10: final_norm weights kept resident in registers (no per-row reload waits); on top of G1 tile-boundary peel
# speedup vs baseline: 1.0208x; 1.0208x over previous
.LBB0_964:
	s_cmp_gt_i32 s58, 10
	s_cselect_b64 s[2:3], -1, 0
	s_xor_b64 s[0:1], s[0:1], -1
	s_or_b64 s[0:1], s[2:3], s[0:1]
	s_and_b64 vcc, exec, s[0:1]
	s_cbranch_vccnz .LBB0_978
	s_mov_b32 s4, 0x8000
	v_cmp_gt_i32_e32 vcc, s4, v146
	s_and_saveexec_b64 s[0:1], vcc
	s_cbranch_execz .LBB0_978
	v_mbcnt_lo_u32_b32 v1, -1, 0
	v_mbcnt_hi_u32_b32 v1, -1, v1
	s_waitcnt vmcnt(0)
	v_and_b32_e32 v3, 64, v1
	v_add_u32_e32 v3, 64, v3
	v_xor_b32_e32 v5, 32, v1
	v_cmp_lt_i32_e32 vcc, v5, v3
	v_and_b32_e32 v0, 0x3ff, v0
	v_lshlrev_b32_e32 v0, 3, v0
	v_cndmask_b32_e32 v5, v1, v5, vcc
	v_lshlrev_b32_e32 v72, 2, v5
	v_xor_b32_e32 v5, 16, v1
	v_cmp_lt_i32_e32 vcc, v5, v3
	v_and_b32_e32 v0, 0x1f8, v0
	v_mov_b32_e32 v49, 0
	v_cndmask_b32_e32 v5, v1, v5, vcc
	v_lshlrev_b32_e32 v73, 2, v5
	v_xor_b32_e32 v5, 8, v1
	v_cmp_lt_i32_e32 vcc, v5, v3
	v_or_b32_e32 v2, 0x400, v0
	v_lshlrev_b32_e32 v48, 2, v0
	v_cndmask_b32_e32 v5, v1, v5, vcc
	v_lshlrev_b32_e32 v74, 2, v5
	v_xor_b32_e32 v5, 4, v1
	v_cmp_lt_i32_e32 vcc, v5, v3
	v_or_b32_e32 v4, 0x600, v0
	v_lshl_add_u64 v[50:51], s[52:53], 0, v[48:49]
	v_cndmask_b32_e32 v5, v1, v5, vcc
	v_lshlrev_b32_e32 v75, 2, v5
	v_xor_b32_e32 v5, 2, v1
	v_cmp_lt_i32_e32 vcc, v5, v3
	v_lshlrev_b32_e32 v48, 2, v2
	v_lshl_add_u64 v[52:53], s[52:53], 0, v[48:49]
	v_cndmask_b32_e32 v5, v1, v5, vcc
	v_lshlrev_b32_e32 v76, 2, v5
	v_xor_b32_e32 v5, 1, v1
	v_lshlrev_b32_e32 v48, 2, v4
	v_cmp_lt_i32_e32 vcc, v5, v3
	v_lshl_add_u64 v[54:55], s[52:53], 0, v[48:49]
	v_lshlrev_b32_e32 v48, 1, v0
	v_cndmask_b32_e32 v1, v1, v5, vcc
	v_lshl_add_u64 v[6:7], s[56:57], 0, v[48:49]
	s_mov_b64 s[0:1], 0x8000000
	v_lshlrev_b32_e32 v58, 2, v2
	v_lshlrev_b32_e32 v62, 2, v4
	s_lshl_b32 s5, s28, 3
	v_lshlrev_b32_e32 v77, 2, v1
	v_lshl_add_u64 v[56:57], v[6:7], 0, s[0:1]
	s_mov_b64 s[0:1], 0
	s_movk_i32 s6, 0x3fff
	v_lshlrev_b32_e32 v48, 2, v0
	v_mov_b32_e32 v60, v58
	v_mov_b32_e32 v61, v49
	v_mov_b32_e32 v64, v62
	v_mov_b32_e32 v65, v49
	v_mov_b32_e32 v78, 0x358637bd
	s_mov_b32 s7, 0x800000
	s_movk_i32 s8, 0x7fff
	global_load_dwordx4 v[160:163], v[50:51], off
	global_load_dwordx4 v[164:167], v[50:51], off offset:16
	global_load_dwordx4 v[168:171], v[50:51], off offset:2048
	global_load_dwordx4 v[172:175], v[50:51], off offset:2064
	global_load_dwordx4 v[176:179], v[52:53], off
	global_load_dwordx4 v[180:183], v[52:53], off offset:16
	global_load_dwordx4 v[184:187], v[54:55], off
	global_load_dwordx4 v[188:191], v[54:55], off offset:16
	s_branch .LBB0_968

.LBB0_968:
	v_cmp_lt_i32_e32 vcc, s6, v146
	s_and_saveexec_b64 s[2:3], vcc
	s_xor_b64 s[2:3], exec, s[2:3]
	v_add_u32_e32 v0, 0xffffc000, v146
	v_mov_b32_e32 v1, v49
	v_lshlrev_b64 v[0:1], 13, v[0:1]
	v_lshl_add_u64 v[4:5], s[14:15], 0, v[0:1]
	v_mov_b32_e32 v147, v49
	s_andn2_saveexec_b64 s[2:3], s[2:3]
	v_ashrrev_i32_e32 v147, 31, v146
	v_lshlrev_b64 v[0:1], 13, v[146:147]
	v_lshl_add_u64 v[4:5], s[12:13], 0, v[0:1]
	s_or_b64 exec, exec, s[2:3]
	v_lshlrev_b64 v[0:1], 12, v[146:147]
	v_lshl_add_u64 v[6:7], v[56:57], 0, v[0:1]
	v_lshl_add_u64 v[0:1], v[4:5], 0, v[48:49]
	global_load_dwordx4 v[44:47], v[0:1], off offset:16 nt
	global_load_dwordx4 v[36:39], v[0:1], off nt
	global_load_dwordx4 v[40:43], v[6:7], off nt
	global_load_dwordx4 v[28:31], v[6:7], off offset:1024 nt
	global_load_dwordx4 v[32:35], v[0:1], off offset:2064 nt
	global_load_dwordx4 v[24:27], v[0:1], off offset:2048 nt
	v_lshl_add_u64 v[8:9], v[4:5], 0, v[60:61]
	global_load_dwordx4 v[20:23], v[8:9], off offset:16 nt
	global_load_dwordx4 v[12:15], v[8:9], off nt
	global_load_dwordx4 v[16:19], v[6:7], off offset:2048 nt
	global_load_dwordx4 v[0:3], v[6:7], off offset:3072 nt
	v_lshl_add_u64 v[66:67], v[4:5], 0, v[64:65]
	global_load_dwordx4 v[8:11], v[66:67], off offset:16 nt
	global_load_dwordx4 v[4:7], v[66:67], off nt
	v_add_u32_e32 v66, s5, v146
	v_cmp_gt_i32_e32 vcc, s4, v66
	s_nop 1
	v_cndmask_b32_e32 v70, v146, v66, vcc
	v_cmp_lt_i32_e32 vcc, s6, v70
	s_and_saveexec_b64 s[2:3], vcc
	s_xor_b64 s[2:3], exec, s[2:3]
	v_add_u32_e32 v68, 0xffffc000, v70
	v_mov_b32_e32 v69, v49
	v_lshlrev_b64 v[68:69], 13, v[68:69]
	v_lshl_add_u64 v[68:69], s[14:15], 0, v[68:69]
	v_mov_b32_e32 v71, v49
	s_andn2_saveexec_b64 s[2:3], s[2:3]
	v_ashrrev_i32_e32 v71, 31, v70
	v_lshlrev_b64 v[68:69], 13, v[70:71]
	v_lshl_add_u64 v[68:69], s[12:13], 0, v[68:69]
	s_or_b64 exec, exec, s[2:3]
	s_waitcnt vmcnt(0)
	v_lshlrev_b32_e32 v88, 16, v42
	v_and_b32_e32 v89, 0xffff0000, v42
	v_lshlrev_b32_e32 v42, 16, v43
	v_and_b32_e32 v43, 0xffff0000, v43
	v_pk_add_f32 v[90:91], v[46:47], v[42:43]
	v_lshlrev_b32_e32 v46, 16, v40
	v_and_b32_e32 v47, 0xffff0000, v40
	v_lshlrev_b32_e32 v40, 16, v41
	v_and_b32_e32 v41, 0xffff0000, v41
	v_pk_add_f32 v[94:95], v[38:39], v[40:41]
	v_lshlrev_b32_e32 v40, 16, v30
	v_and_b32_e32 v41, 0xffff0000, v30
	v_lshlrev_b32_e32 v30, 16, v31
	v_and_b32_e32 v31, 0xffff0000, v31
	v_pk_add_f32 v[98:99], v[34:35], v[30:31]
	v_lshlrev_b32_e32 v34, 16, v28
	v_and_b32_e32 v35, 0xffff0000, v28
	v_lshlrev_b32_e32 v28, 16, v29
	v_and_b32_e32 v29, 0xffff0000, v29
	v_pk_add_f32 v[102:103], v[26:27], v[28:29]
	v_lshlrev_b32_e32 v28, 16, v18
	v_and_b32_e32 v29, 0xffff0000, v18
	v_lshlrev_b32_e32 v18, 16, v19
	v_and_b32_e32 v19, 0xffff0000, v19
	v_mov_b64_e32 v[80:81], v[164:165]
	v_mov_b64_e32 v[82:83], v[166:167]
	v_mov_b64_e32 v[84:85], v[160:161]
	v_mov_b64_e32 v[86:87], v[162:163]
	v_pk_add_f32 v[106:107], v[22:23], v[18:19]
	v_lshlrev_b32_e32 v22, 16, v16
	v_and_b32_e32 v23, 0xffff0000, v16
	v_lshlrev_b32_e32 v16, 16, v17
	v_and_b32_e32 v17, 0xffff0000, v17
	v_pk_add_f32 v[92:93], v[36:37], v[46:47]
	v_pk_add_f32 v[110:111], v[14:15], v[16:17]
	v_lshlrev_b32_e32 v16, 16, v2
	v_and_b32_e32 v17, 0xffff0000, v2
	v_lshlrev_b32_e32 v2, 16, v3
	v_and_b32_e32 v3, 0xffff0000, v3
	v_pk_mul_f32 v[36:37], v[92:93], v[92:93]
	v_pk_add_f32 v[114:115], v[10:11], v[2:3]
	v_lshlrev_b32_e32 v10, 16, v0
	v_and_b32_e32 v11, 0xffff0000, v0
	v_lshlrev_b32_e32 v0, 16, v1
	v_and_b32_e32 v1, 0xffff0000, v1
	v_pk_mul_f32 v[38:39], v[94:95], v[94:95]
	v_pk_add_f32 v[118:119], v[6:7], v[0:1]
	v_add_f32_e32 v6, v36, v37
	v_pk_add_f32 v[88:89], v[44:45], v[88:89]
	v_add_f32_e32 v6, v38, v6
	v_pk_mul_f32 v[44:45], v[88:89], v[88:89]
	v_add_f32_e32 v6, v39, v6
	v_add_f32_e32 v6, v44, v6
	v_pk_mul_f32 v[42:43], v[90:91], v[90:91]
	v_add_f32_e32 v6, v45, v6
	v_pk_add_f32 v[100:101], v[24:25], v[34:35]
	v_add_f32_e32 v6, v42, v6
	v_pk_mul_f32 v[24:25], v[100:101], v[100:101]
	v_add_f32_e32 v6, v43, v6
	v_add_f32_e32 v6, v24, v6
	v_pk_mul_f32 v[26:27], v[102:103], v[102:103]
	v_add_f32_e32 v6, v25, v6
	v_pk_add_f32 v[96:97], v[32:33], v[40:41]
	v_add_f32_e32 v6, v26, v6
	v_pk_mul_f32 v[32:33], v[96:97], v[96:97]
	v_add_f32_e32 v6, v27, v6
	v_add_f32_e32 v6, v32, v6
	v_pk_mul_f32 v[30:31], v[98:99], v[98:99]
	v_add_f32_e32 v6, v33, v6
	v_pk_add_f32 v[108:109], v[12:13], v[22:23]
	v_add_f32_e32 v6, v30, v6
	v_pk_mul_f32 v[12:13], v[108:109], v[108:109]
	v_add_f32_e32 v6, v31, v6
	v_add_f32_e32 v6, v12, v6
	v_pk_mul_f32 v[14:15], v[110:111], v[110:111]
	v_add_f32_e32 v6, v13, v6
	v_pk_add_f32 v[104:105], v[20:21], v[28:29]
	v_add_f32_e32 v6, v14, v6
	v_pk_mul_f32 v[20:21], v[104:105], v[104:105]
	v_add_f32_e32 v6, v15, v6
	v_add_f32_e32 v6, v20, v6
	v_pk_mul_f32 v[18:19], v[106:107], v[106:107]
	v_add_f32_e32 v6, v21, v6
	v_pk_add_f32 v[116:117], v[4:5], v[10:11]
	v_add_f32_e32 v6, v18, v6
	v_pk_mul_f32 v[4:5], v[116:117], v[116:117]
	v_add_f32_e32 v6, v19, v6
	v_add_f32_e32 v4, v4, v6
	v_pk_mul_f32 v[0:1], v[118:119], v[118:119]
	v_add_f32_e32 v4, v5, v4
	v_pk_add_f32 v[112:113], v[8:9], v[16:17]
	v_add_f32_e32 v0, v0, v4
	v_pk_mul_f32 v[8:9], v[112:113], v[112:113]
	v_add_f32_e32 v0, v1, v0
	v_add_f32_e32 v0, v8, v0
	v_pk_mul_f32 v[2:3], v[114:115], v[114:115]
	v_add_f32_e32 v0, v9, v0
	v_add_f32_e32 v0, v2, v0
	v_add_f32_e32 v0, v3, v0
	ds_bpermute_b32 v1, v72, v0
	v_mov_b32_e32 v59, v49
	v_mov_b32_e32 v63, v49
	v_lshl_add_u64 v[6:7], v[68:69], 0, v[58:59]
	s_waitcnt lgkmcnt(0)
	v_add_f32_e32 v2, v0, v1
	ds_bpermute_b32 v3, v73, v2
	v_lshlrev_b64 v[0:1], 12, v[70:71]
	v_lshl_add_u64 v[4:5], v[56:57], 0, v[0:1]
	v_lshl_add_u64 v[0:1], v[68:69], 0, v[48:49]
	v_lshl_add_u64 v[68:69], v[68:69], 0, v[62:63]
	s_waitcnt lgkmcnt(0)
	v_add_f32_e32 v2, v2, v3
	ds_bpermute_b32 v3, v74, v2
	global_load_dwordx4 v[44:47], v[0:1], off offset:16 nt
	global_load_dwordx4 v[36:39], v[0:1], off nt
	global_load_dwordx4 v[40:43], v[4:5], off nt
	global_load_dwordx4 v[28:31], v[4:5], off offset:1024 nt
	global_load_dwordx4 v[32:35], v[0:1], off offset:2064 nt
	global_load_dwordx4 v[24:27], v[0:1], off offset:2048 nt
	s_waitcnt lgkmcnt(0)
	v_add_f32_e32 v2, v2, v3
	ds_bpermute_b32 v3, v75, v2
	s_waitcnt lgkmcnt(0)
	v_add_f32_e32 v8, v2, v3
	ds_bpermute_b32 v9, v76, v8
	global_load_dwordx4 v[20:23], v[6:7], off offset:16 nt
	global_load_dwordx4 v[12:15], v[6:7], off nt
	global_load_dwordx4 v[16:19], v[4:5], off offset:2048 nt
	global_load_dwordx4 v[0:3], v[4:5], off offset:3072 nt
	s_waitcnt lgkmcnt(0)
	v_add_f32_e32 v67, v8, v9
	ds_bpermute_b32 v70, v77, v67
	global_load_dwordx4 v[8:11], v[68:69], off offset:16 nt
	global_load_dwordx4 v[4:7], v[68:69], off nt
	s_waitcnt lgkmcnt(0)
	v_add_f32_e32 v67, v67, v70
	v_fmamk_f32 v67, v67, 0x3a000000, v78
	v_mul_f32_e32 v68, 0x4b800000, v67
	v_cmp_gt_f32_e32 vcc, s7, v67
	s_nop 1
	v_cndmask_b32_e32 v67, v67, v68, vcc
	v_rsq_f32_e32 v67, v67
	v_lshlrev_b64 v[68:69], 13, v[146:147]
	v_lshl_add_u64 v[120:121], s[54:55], 0, v[68:69]
	v_lshl_add_u64 v[122:123], v[120:121], 0, v[48:49]
	v_mul_f32_e32 v68, 0x45800000, v67
	v_cndmask_b32_e32 v124, v67, v68, vcc
	v_pk_mul_f32 v[68:69], v[92:93], v[124:125] op_sel_hi:[1,0]
	v_pk_mul_f32 v[70:71], v[94:95], v[124:125] op_sel_hi:[1,0]
	v_pk_mul_f32 v[68:69], v[84:85], v[68:69]
	v_pk_mul_f32 v[70:71], v[86:87], v[70:71]
	v_pk_mul_f32 v[84:85], v[88:89], v[124:125] op_sel_hi:[1,0]
	v_pk_mul_f32 v[86:87], v[90:91], v[124:125] op_sel_hi:[1,0]
	v_pk_mul_f32 v[80:81], v[80:81], v[84:85]
	v_pk_mul_f32 v[82:83], v[82:83], v[86:87]
	global_store_dwordx4 v[122:123], v[68:71], off nt
	global_store_dwordx4 v[122:123], v[80:83], off offset:16 nt
	s_nop 1
	v_mov_b64_e32 v[68:69], v[168:169]
	v_mov_b64_e32 v[70:71], v[170:171]
	s_nop 0
	v_mov_b64_e32 v[80:81], v[172:173]
	v_mov_b64_e32 v[82:83], v[174:175]
	v_pk_mul_f32 v[84:85], v[102:103], v[124:125] op_sel_hi:[1,0]
	v_pk_mul_f32 v[86:87], v[100:101], v[124:125] op_sel_hi:[1,0]
	v_pk_mul_f32 v[88:89], v[98:99], v[124:125] op_sel_hi:[1,0]
	v_pk_mul_f32 v[90:91], v[96:97], v[124:125] op_sel_hi:[1,0]
	v_pk_mul_f32 v[92:93], v[104:105], v[124:125] op_sel_hi:[1,0]
	v_cmp_gt_i32_e32 vcc, s4, v66
	v_pk_mul_f32 v[68:69], v[68:69], v[86:87]
	v_pk_mul_f32 v[70:71], v[70:71], v[84:85]
	v_pk_mul_f32 v[80:81], v[80:81], v[90:91]
	v_pk_mul_f32 v[82:83], v[82:83], v[88:89]
	global_store_dwordx4 v[122:123], v[68:71], off offset:2048 nt
	global_store_dwordx4 v[122:123], v[80:83], off offset:2064 nt
	s_nop 1
	v_mov_b64_e32 v[68:69], v[176:177]
	v_mov_b64_e32 v[70:71], v[178:179]
	s_nop 0
	v_mov_b64_e32 v[80:81], v[180:181]
	v_mov_b64_e32 v[82:83], v[182:183]
	v_pk_mul_f32 v[86:87], v[110:111], v[124:125] op_sel_hi:[1,0]
	v_pk_mul_f32 v[88:89], v[108:109], v[124:125] op_sel_hi:[1,0]
	v_lshl_add_u64 v[84:85], v[120:121], 0, v[58:59]
	v_pk_mul_f32 v[90:91], v[106:107], v[124:125] op_sel_hi:[1,0]
	v_pk_mul_f32 v[68:69], v[68:69], v[88:89]
	v_pk_mul_f32 v[70:71], v[70:71], v[86:87]
	v_pk_mul_f32 v[80:81], v[92:93], v[80:81]
	v_pk_mul_f32 v[82:83], v[90:91], v[82:83]
	global_store_dwordx4 v[84:85], v[68:71], off nt
	global_store_dwordx4 v[84:85], v[80:83], off offset:16 nt
	s_nop 1
	v_mov_b64_e32 v[68:69], v[184:185]
	v_mov_b64_e32 v[70:71], v[186:187]
	s_nop 0
	v_mov_b64_e32 v[80:81], v[188:189]
	v_mov_b64_e32 v[82:83], v[190:191]
	v_pk_mul_f32 v[86:87], v[118:119], v[124:125] op_sel_hi:[1,0]
	v_pk_mul_f32 v[88:89], v[116:117], v[124:125] op_sel_hi:[1,0]
	v_lshl_add_u64 v[84:85], v[120:121], 0, v[62:63]
	v_pk_mul_f32 v[90:91], v[114:115], v[124:125] op_sel_hi:[1,0]
	v_pk_mul_f32 v[92:93], v[112:113], v[124:125] op_sel_hi:[1,0]
	v_pk_mul_f32 v[68:69], v[88:89], v[68:69]
	v_pk_mul_f32 v[70:71], v[86:87], v[70:71]
	v_pk_mul_f32 v[80:81], v[92:93], v[80:81]
	v_pk_mul_f32 v[82:83], v[90:91], v[82:83]
	global_store_dwordx4 v[84:85], v[68:71], off nt
	global_store_dwordx4 v[84:85], v[80:83], off offset:16 nt
	s_and_saveexec_b64 s[2:3], vcc
	s_cbranch_execz .LBB0_967
	s_waitcnt vmcnt(8)
	v_mov_b64_e32 v[68:69], v[164:165]
	v_mov_b64_e32 v[70:71], v[166:167]
	v_mov_b64_e32 v[80:81], v[160:161]
	v_mov_b64_e32 v[82:83], v[162:163]
	v_lshlrev_b32_e32 v86, 16, v40
	v_and_b32_e32 v87, 0xffff0000, v40
	v_pk_add_f32 v[36:37], v[36:37], v[86:87]
	v_lshlrev_b32_e32 v40, 16, v41
	v_and_b32_e32 v41, 0xffff0000, v41
	v_pk_mul_f32 v[86:87], v[36:37], v[36:37]
	v_pk_add_f32 v[38:39], v[38:39], v[40:41]
	v_lshlrev_b32_e32 v98, 16, v0
	v_and_b32_e32 v99, 0xffff0000, v0
	v_lshlrev_b32_e32 v0, 16, v1
	v_and_b32_e32 v1, 0xffff0000, v1
	v_lshlrev_b32_e32 v84, 16, v42
	v_and_b32_e32 v85, 0xffff0000, v42
	v_pk_mul_f32 v[40:41], v[38:39], v[38:39]
	v_pk_add_f32 v[100:101], v[6:7], v[0:1]
	v_add_f32_e32 v6, v86, v87
	v_pk_add_f32 v[44:45], v[44:45], v[84:85]
	v_add_f32_e32 v6, v40, v6
	v_pk_mul_f32 v[84:85], v[44:45], v[44:45]
	v_lshlrev_b32_e32 v42, 16, v43
	v_and_b32_e32 v43, 0xffff0000, v43
	v_add_f32_e32 v6, v41, v6
	v_pk_add_f32 v[42:43], v[46:47], v[42:43]
	v_add_f32_e32 v6, v84, v6
	v_pk_mul_f32 v[46:47], v[42:43], v[42:43]
	v_lshlrev_b32_e32 v90, 16, v28
	v_and_b32_e32 v91, 0xffff0000, v28
	v_add_f32_e32 v6, v85, v6
	v_pk_add_f32 v[24:25], v[24:25], v[90:91]
	v_add_f32_e32 v6, v46, v6
	v_pk_mul_f32 v[90:91], v[24:25], v[24:25]
	v_lshlrev_b32_e32 v28, 16, v29
	v_and_b32_e32 v29, 0xffff0000, v29
	v_add_f32_e32 v6, v47, v6
	v_pk_add_f32 v[26:27], v[26:27], v[28:29]
	v_add_f32_e32 v6, v90, v6
	v_lshlrev_b32_e32 v88, 16, v30
	v_and_b32_e32 v89, 0xffff0000, v30
	v_pk_mul_f32 v[28:29], v[26:27], v[26:27]
	v_add_f32_e32 v6, v91, v6
	v_pk_add_f32 v[32:33], v[32:33], v[88:89]
	v_add_f32_e32 v6, v28, v6
	v_pk_mul_f32 v[88:89], v[32:33], v[32:33]
	v_lshlrev_b32_e32 v30, 16, v31
	v_and_b32_e32 v31, 0xffff0000, v31
	v_add_f32_e32 v6, v29, v6
	v_pk_add_f32 v[30:31], v[34:35], v[30:31]
	v_add_f32_e32 v6, v88, v6
	v_pk_mul_f32 v[34:35], v[30:31], v[30:31]
	v_lshlrev_b32_e32 v94, 16, v16
	v_and_b32_e32 v95, 0xffff0000, v16
	v_add_f32_e32 v6, v89, v6
	v_pk_add_f32 v[12:13], v[12:13], v[94:95]
	v_add_f32_e32 v6, v34, v6
	v_pk_mul_f32 v[94:95], v[12:13], v[12:13]
	v_lshlrev_b32_e32 v16, 16, v17
	v_and_b32_e32 v17, 0xffff0000, v17
	v_add_f32_e32 v6, v35, v6
	v_pk_add_f32 v[14:15], v[14:15], v[16:17]
	v_add_f32_e32 v6, v94, v6
	v_lshlrev_b32_e32 v92, 16, v18
	v_and_b32_e32 v93, 0xffff0000, v18
	v_pk_mul_f32 v[16:17], v[14:15], v[14:15]
	v_add_f32_e32 v6, v95, v6
	v_pk_add_f32 v[20:21], v[20:21], v[92:93]
	v_add_f32_e32 v6, v16, v6
	v_pk_mul_f32 v[92:93], v[20:21], v[20:21]
	v_lshlrev_b32_e32 v18, 16, v19
	v_and_b32_e32 v19, 0xffff0000, v19
	v_add_f32_e32 v6, v17, v6
	v_pk_add_f32 v[18:19], v[22:23], v[18:19]
	v_add_f32_e32 v6, v92, v6
	v_pk_mul_f32 v[22:23], v[18:19], v[18:19]
	v_add_f32_e32 v6, v93, v6
	v_pk_add_f32 v[98:99], v[4:5], v[98:99]
	v_add_f32_e32 v6, v22, v6
	v_pk_mul_f32 v[4:5], v[98:99], v[98:99]
	v_add_f32_e32 v6, v23, v6
	v_add_f32_e32 v4, v4, v6
	v_lshlrev_b32_e32 v96, 16, v2
	v_and_b32_e32 v97, 0xffff0000, v2
	v_pk_mul_f32 v[0:1], v[100:101], v[100:101]
	v_add_f32_e32 v4, v5, v4
	v_pk_add_f32 v[8:9], v[8:9], v[96:97]
	v_add_f32_e32 v0, v0, v4
	v_pk_mul_f32 v[96:97], v[8:9], v[8:9]
	v_lshlrev_b32_e32 v2, 16, v3
	v_and_b32_e32 v3, 0xffff0000, v3
	v_add_f32_e32 v0, v1, v0
	v_pk_add_f32 v[10:11], v[10:11], v[2:3]
	v_add_f32_e32 v0, v96, v0
	v_pk_mul_f32 v[2:3], v[10:11], v[10:11]
	v_add_f32_e32 v0, v97, v0
	v_add_f32_e32 v0, v2, v0
	v_add_f32_e32 v0, v3, v0
	ds_bpermute_b32 v1, v72, v0
	v_ashrrev_i32_e32 v67, 31, v66
	s_waitcnt lgkmcnt(0)
	v_add_f32_e32 v0, v0, v1
	ds_bpermute_b32 v1, v73, v0
	s_waitcnt lgkmcnt(0)
	v_add_f32_e32 v0, v0, v1
	ds_bpermute_b32 v1, v74, v0
	s_waitcnt lgkmcnt(0)
	v_add_f32_e32 v0, v0, v1
	ds_bpermute_b32 v1, v75, v0
	s_waitcnt lgkmcnt(0)
	v_add_f32_e32 v0, v0, v1
	ds_bpermute_b32 v1, v76, v0
	s_waitcnt lgkmcnt(0)
	v_add_f32_e32 v0, v0, v1
	ds_bpermute_b32 v1, v77, v0
	s_waitcnt lgkmcnt(0)
	v_add_f32_e32 v0, v0, v1
	v_fmamk_f32 v0, v0, 0x3a000000, v78
	v_mul_f32_e32 v1, 0x4b800000, v0
	v_cmp_gt_f32_e32 vcc, s7, v0
	s_nop 1
	v_cndmask_b32_e32 v0, v0, v1, vcc
	v_rsq_f32_e32 v2, v0
	v_lshlrev_b64 v[0:1], 13, v[66:67]
	v_lshl_add_u64 v[16:17], s[54:55], 0, v[0:1]
	v_lshl_add_u64 v[22:23], v[16:17], 0, v[48:49]
	v_mul_f32_e32 v0, 0x45800000, v2
	v_cndmask_b32_e32 v28, v2, v0, vcc
	v_pk_mul_f32 v[0:1], v[36:37], v[28:29] op_sel_hi:[1,0]
	v_pk_mul_f32 v[2:3], v[38:39], v[28:29] op_sel_hi:[1,0]
	v_pk_mul_f32 v[0:1], v[80:81], v[0:1]
	v_pk_mul_f32 v[2:3], v[82:83], v[2:3]
	v_pk_mul_f32 v[4:5], v[44:45], v[28:29] op_sel_hi:[1,0]
	v_pk_mul_f32 v[6:7], v[42:43], v[28:29] op_sel_hi:[1,0]
	v_pk_mul_f32 v[4:5], v[68:69], v[4:5]
	v_pk_mul_f32 v[6:7], v[70:71], v[6:7]
	global_store_dwordx4 v[22:23], v[0:3], off nt
	global_store_dwordx4 v[22:23], v[4:7], off offset:16 nt
	s_nop 1
	v_mov_b64_e32 v[0:1], v[168:169]
	v_mov_b64_e32 v[2:3], v[170:171]
	s_nop 0
	v_mov_b64_e32 v[4:5], v[172:173]
	v_mov_b64_e32 v[6:7], v[174:175]
	v_pk_mul_f32 v[26:27], v[26:27], v[28:29] op_sel_hi:[1,0]
	v_pk_mul_f32 v[24:25], v[24:25], v[28:29] op_sel_hi:[1,0]
	v_pk_mul_f32 v[30:31], v[30:31], v[28:29] op_sel_hi:[1,0]
	v_pk_mul_f32 v[32:33], v[32:33], v[28:29] op_sel_hi:[1,0]
	v_pk_mul_f32 v[14:15], v[14:15], v[28:29] op_sel_hi:[1,0]
	v_pk_mul_f32 v[12:13], v[12:13], v[28:29] op_sel_hi:[1,0]
	v_pk_mul_f32 v[18:19], v[18:19], v[28:29] op_sel_hi:[1,0]
	v_pk_mul_f32 v[20:21], v[20:21], v[28:29] op_sel_hi:[1,0]
	v_pk_mul_f32 v[10:11], v[10:11], v[28:29] op_sel_hi:[1,0]
	v_pk_mul_f32 v[8:9], v[8:9], v[28:29] op_sel_hi:[1,0]
	v_pk_mul_f32 v[0:1], v[0:1], v[24:25]
	v_pk_mul_f32 v[2:3], v[2:3], v[26:27]
	v_pk_mul_f32 v[4:5], v[4:5], v[32:33]
	v_pk_mul_f32 v[6:7], v[6:7], v[30:31]
	global_store_dwordx4 v[22:23], v[0:3], off offset:2048 nt
	global_store_dwordx4 v[22:23], v[4:7], off offset:2064 nt
	s_nop 1
	v_mov_b64_e32 v[0:1], v[176:177]
	v_mov_b64_e32 v[2:3], v[178:179]
	s_nop 0
	v_mov_b64_e32 v[4:5], v[180:181]
	v_mov_b64_e32 v[6:7], v[182:183]
	v_lshl_add_u64 v[22:23], v[16:17], 0, v[58:59]
	v_pk_mul_f32 v[0:1], v[0:1], v[12:13]
	v_pk_mul_f32 v[2:3], v[2:3], v[14:15]
	v_pk_mul_f32 v[4:5], v[20:21], v[4:5]
	v_pk_mul_f32 v[6:7], v[18:19], v[6:7]
	global_store_dwordx4 v[22:23], v[0:3], off nt
	global_store_dwordx4 v[22:23], v[4:7], off offset:16 nt
	s_nop 1
	v_mov_b64_e32 v[0:1], v[184:185]
	v_mov_b64_e32 v[2:3], v[186:187]
	s_nop 0
	v_mov_b64_e32 v[4:5], v[188:189]
	v_mov_b64_e32 v[6:7], v[190:191]
	v_lshl_add_u64 v[12:13], v[16:17], 0, v[62:63]
	v_pk_mul_f32 v[14:15], v[100:101], v[28:29] op_sel_hi:[1,0]
	v_pk_mul_f32 v[16:17], v[98:99], v[28:29] op_sel_hi:[1,0]
	v_pk_mul_f32 v[2:3], v[14:15], v[2:3]
	v_pk_mul_f32 v[0:1], v[16:17], v[0:1]
	v_pk_mul_f32 v[4:5], v[8:9], v[4:5]
	v_pk_mul_f32 v[6:7], v[10:11], v[6:7]
	global_store_dwordx4 v[12:13], v[0:3], off nt
	global_store_dwordx4 v[12:13], v[4:7], off offset:16 nt
	s_branch .LBB0_967
